# states phase: WST rows staged in LDS once per item; 64 serialized global loads per item become LDS reads
# speedup vs baseline: 1.0094x; 1.0094x over previous
.LBB0_1976:
	s_or_b64 exec, exec, s[0:1]
	s_add_u32 s0, s10, 0x9210000
	s_addc_u32 s1, s11, 0
	v_writelane_b32 v252, s0, 49
	v_mov_b32_e32 v65, v218
	s_waitcnt lgkmcnt(0)
	v_mov_b32_e32 v0, v219
	v_writelane_b32 v252, s1, 50
	s_mov_b64 s[0:1], s[60:61]
	s_barrier
	s_nop 0
	v_readfirstlane_b32 s16, v0
	s_cmpk_gt_i32 s16, 0x3ff
	s_cbranch_scc1 .LBB0_1987
	s_load_dwordx2 s[0:1], s[0:1], 0xe8
	s_movk_i32 s2, 0x800
	v_bfe_u32 v2, v65, 5, 1
	v_cmp_gt_i32_e32 vcc, s2, v65
	v_readlane_b32 s2, v252, 43
	v_and_b32_e32 v64, 31, v65
	v_lshlrev_b32_e32 v0, 4, v2
	v_mov_b32_e32 v1, v129
	v_readlane_b32 s3, v252, 44
	v_ashrrev_i32_e32 v234, 4, v65
	v_lshlrev_b32_e32 v3, 1, v234
	v_lshl_add_u64 v[66:67], s[2:3], 0, v[0:1]
	v_mul_u32_u24_e32 v1, 0x110, v64
	v_add3_u32 v233, v220, v1, v0
	v_lshlrev_b32_e32 v0, 5, v2
	v_mov_b32_e32 v1, v129
	s_waitcnt lgkmcnt(0)
	v_lshl_add_u64 v[0:1], s[0:1], 0, v[0:1]
	s_mov_b64 s[0:1], 0xd08000
	v_lshl_add_u64 v[68:69], v[0:1], 0, s[0:1]
	v_readlane_b32 s0, v252, 49
	v_lshlrev_b32_e32 v0, 10, v2
	v_mov_b32_e32 v1, v129
	v_readlane_b32 s1, v252, 50
	s_movk_i32 s2, 0xff
	v_add_u32_e32 v236, 0x100, v65
	v_lshl_add_u64 v[70:71], s[0:1], 0, v[0:1]
	v_max_i32_e32 v0, 0x700, v65
	v_sub_u32_e32 v0, v0, v65
	v_add_u32_e32 v1, 0xff, v0
	v_and_b32_e32 v0, 0x100, v1
	v_cmp_eq_u32_e64 s[0:1], 0, v0
	v_lshlrev_b32_e32 v0, 3, v65
	v_and_b32_e32 v0, 0x78, v0
	v_mul_u32_u24_e32 v2, 0x110, v0
	v_add3_u32 v235, v220, v2, v3
	v_cmp_lt_u32_e64 s[2:3], s2, v1
	v_lshlrev_b32_e32 v72, 1, v0
	v_lshrrev_b32_e32 v237, 6, v65
	v_lshlrev_b32_e32 v237, 10, v237
	v_add_u32_e32 v237, v237, v220
	v_add_u32_e32 v237, 0x8800, v237
	v_lshl_add_u32 v253, v221, 3, v237
	v_lshrrev_b32_e32 v254, 5, v221
	v_lshl_add_u32 v237, v254, 5, v237

.LBB0_1984:
	s_or_b64 exec, exec, s[10:11]
	v_ashrrev_i32_e32 v0, 6, v65
	v_lshl_add_u32 v74, s7, 2, v0
	s_ashr_i32 s7, s6, 31
	v_lshlrev_b32_e32 v0, 6, v74
	s_lshl_b64 s[4:5], s[6:7], 11
	v_ashrrev_i32_e32 v1, 31, v0
	v_lshl_add_u64 v[0:1], s[4:5], 0, v[0:1]
	v_or_b32_e32 v0, v0, v64
	v_lshlrev_b64 v[0:1], 8, v[0:1]
	v_lshl_add_u64 v[0:1], v[66:67], 0, v[0:1]
	s_movk_i32 s11, 0x2000
	v_add_co_u32_e64 v2, s[4:5], s11, v0
	s_waitcnt lgkmcnt(0)
	s_nop 0
	v_addc_co_u32_e64 v3, s[4:5], 0, v1, s[4:5]
	s_barrier
	s_load_dwordx2 s[100:101], s[60:61], 0xe8
	v_readfirstlane_b32 s4, v74
	v_lshlrev_b32_e32 v84, 3, v221
	s_lshl_b32 s5, s6, 15
	s_waitcnt lgkmcnt(0)
	s_add_u32 s100, s100, s5
	s_addc_u32 s101, s101, 0
	s_lshl_b32 s4, s4, 9
	s_add_u32 s100, s100, s4
	s_addc_u32 s101, s101, 0
	s_add_u32 s100, s100, 0xd08000
	s_addc_u32 s101, s101, 0
	global_load_dwordx2 v[80:81], v84, s[100:101]
	s_add_u32 s100, s100, 0x4000
	s_addc_u32 s101, s101, 0
	global_load_dwordx2 v[82:83], v84, s[100:101]
	global_load_dwordx4 v[24:27], v[0:1], off
	global_load_dwordx4 v[28:31], v[0:1], off offset:32
	global_load_dwordx4 v[32:35], v[0:1], off offset:64
	global_load_dwordx4 v[36:39], v[0:1], off offset:96
	global_load_dwordx4 v[40:43], v[2:3], off
	global_load_dwordx4 v[44:47], v[2:3], off offset:32
	global_load_dwordx4 v[48:51], v[2:3], off offset:64
	global_load_dwordx4 v[52:55], v[2:3], off offset:96
	global_load_dwordx4 v[56:59], v[0:1], off offset:128
	global_load_dwordx4 v[60:63], v[2:3], off offset:128
	global_load_dwordx4 v[20:23], v[0:1], off offset:160
	global_load_dwordx4 v[12:15], v[0:1], off offset:192
	global_load_dwordx4 v[4:7], v[0:1], off offset:224
	global_load_dwordx4 v[16:19], v[2:3], off offset:160
	global_load_dwordx4 v[8:11], v[2:3], off offset:192
	s_nop 0
	global_load_dwordx4 v[0:3], v[2:3], off offset:224
	s_lshl_b64 s[4:5], s[6:7], 15
	s_lshl_b64 s[6:7], s[6:7], 6
	v_ashrrev_i32_e32 v75, 31, v74
	v_readlane_b32 s14, v252, 12
	s_mov_b32 s10, 0
	v_lshl_add_u64 v[76:77], v[68:69], 0, s[4:5]
	v_lshl_add_u64 v[78:79], s[6:7], 0, v[74:75]
	s_mov_b32 s6, 0
	s_movk_i32 s7, 0x3000
	s_movk_i32 s12, 0x1000
	v_readlane_b32 s15, v252, 13
	s_waitcnt vmcnt(16)
	ds_write_b64 v253, v[80:81]
	ds_write_b64 v253, v[82:83] offset:512
	s_waitcnt vmcnt(15)
	v_lshlrev_b32_e32 v80, 16, v24
	v_and_b32_e32 v81, 0xffff0000, v24
	v_lshlrev_b32_e32 v82, 16, v25
	v_and_b32_e32 v83, 0xffff0000, v25
	v_lshlrev_b32_e32 v84, 16, v26
	v_and_b32_e32 v85, 0xffff0000, v26
	v_lshlrev_b32_e32 v86, 16, v27
	v_and_b32_e32 v87, 0xffff0000, v27
	s_waitcnt vmcnt(14)
	v_lshlrev_b32_e32 v88, 16, v28
	v_and_b32_e32 v89, 0xffff0000, v28
	v_lshlrev_b32_e32 v90, 16, v29
	v_and_b32_e32 v91, 0xffff0000, v29
	v_lshlrev_b32_e32 v92, 16, v30
	v_and_b32_e32 v93, 0xffff0000, v30
	v_lshlrev_b32_e32 v94, 16, v31
	v_and_b32_e32 v95, 0xffff0000, v31
	s_waitcnt vmcnt(13)
	v_lshlrev_b32_e32 v96, 16, v32
	v_and_b32_e32 v97, 0xffff0000, v32
	v_lshlrev_b32_e32 v98, 16, v33
	v_and_b32_e32 v99, 0xffff0000, v33
	v_lshlrev_b32_e32 v100, 16, v34
	v_and_b32_e32 v101, 0xffff0000, v34
	v_lshlrev_b32_e32 v102, 16, v35
	v_and_b32_e32 v103, 0xffff0000, v35
	s_waitcnt vmcnt(12)
	v_lshlrev_b32_e32 v104, 16, v36
	v_and_b32_e32 v105, 0xffff0000, v36
	v_lshlrev_b32_e32 v106, 16, v37
	s_waitcnt vmcnt(11)
	v_lshlrev_b32_e32 v108, 16, v40
	v_and_b32_e32 v109, 0xffff0000, v40
	v_lshlrev_b32_e32 v110, 16, v41
	v_and_b32_e32 v111, 0xffff0000, v41
	v_lshlrev_b32_e32 v112, 16, v42
	v_and_b32_e32 v113, 0xffff0000, v42
	v_lshlrev_b32_e32 v114, 16, v43
	v_and_b32_e32 v115, 0xffff0000, v43
	s_waitcnt vmcnt(10)
	v_lshlrev_b32_e32 v116, 16, v44
	v_and_b32_e32 v117, 0xffff0000, v44
	v_lshlrev_b32_e32 v118, 16, v45
	v_and_b32_e32 v119, 0xffff0000, v45
	v_lshlrev_b32_e32 v120, 16, v46
	v_and_b32_e32 v121, 0xffff0000, v46
	v_lshlrev_b32_e32 v122, 16, v47
	v_and_b32_e32 v123, 0xffff0000, v47
	s_waitcnt vmcnt(9)
	v_lshlrev_b32_e32 v124, 16, v48
	v_and_b32_e32 v125, 0xffff0000, v48
	v_lshlrev_b32_e32 v126, 16, v49
	v_and_b32_e32 v127, 0xffff0000, v49
	v_lshlrev_b32_e32 v130, 16, v50
	v_and_b32_e32 v131, 0xffff0000, v50
	v_lshlrev_b32_e32 v132, 16, v51
	v_and_b32_e32 v133, 0xffff0000, v51
	v_and_b32_e32 v107, 0xffff0000, v37
	v_lshlrev_b32_e32 v134, 16, v38
	v_and_b32_e32 v135, 0xffff0000, v38
	v_lshlrev_b32_e32 v136, 16, v39
	v_and_b32_e32 v137, 0xffff0000, v39
	s_waitcnt vmcnt(8)
	v_lshlrev_b32_e32 v138, 16, v52
	v_and_b32_e32 v139, 0xffff0000, v52
	v_lshlrev_b32_e32 v140, 16, v53
	v_and_b32_e32 v141, 0xffff0000, v53
	v_lshlrev_b32_e32 v142, 16, v54
	v_and_b32_e32 v143, 0xffff0000, v54
	v_lshlrev_b32_e32 v144, 16, v55
	v_and_b32_e32 v145, 0xffff0000, v55
	s_waitcnt vmcnt(7)
	v_lshlrev_b32_e32 v146, 16, v56
	v_and_b32_e32 v147, 0xffff0000, v56
	v_lshlrev_b32_e32 v148, 16, v57
	v_and_b32_e32 v149, 0xffff0000, v57
	v_lshlrev_b32_e32 v150, 16, v58
	v_and_b32_e32 v151, 0xffff0000, v58
	v_lshlrev_b32_e32 v152, 16, v59
	v_and_b32_e32 v153, 0xffff0000, v59
	s_waitcnt vmcnt(6)
	v_lshlrev_b32_e32 v154, 16, v60
	v_and_b32_e32 v155, 0xffff0000, v60
	v_lshlrev_b32_e32 v156, 16, v61
	v_and_b32_e32 v157, 0xffff0000, v61
	v_lshlrev_b32_e32 v158, 16, v62
	v_and_b32_e32 v159, 0xffff0000, v62
	v_lshlrev_b32_e32 v160, 16, v63
	v_and_b32_e32 v161, 0xffff0000, v63
	s_waitcnt vmcnt(5)
	v_lshlrev_b32_e32 v168, 16, v20
	v_and_b32_e32 v169, 0xffff0000, v20
	v_lshlrev_b32_e32 v170, 16, v21
	v_and_b32_e32 v171, 0xffff0000, v21
	v_lshlrev_b32_e32 v172, 16, v22
	v_and_b32_e32 v173, 0xffff0000, v22
	v_lshlrev_b32_e32 v174, 16, v23
	v_and_b32_e32 v175, 0xffff0000, v23
	s_waitcnt vmcnt(2)
	v_lshlrev_b32_e32 v176, 16, v16
	v_and_b32_e32 v177, 0xffff0000, v16
	v_lshlrev_b32_e32 v178, 16, v17
	v_and_b32_e32 v179, 0xffff0000, v17
	v_lshlrev_b32_e32 v180, 16, v18
	v_and_b32_e32 v181, 0xffff0000, v18
	v_lshlrev_b32_e32 v182, 16, v19
	v_and_b32_e32 v183, 0xffff0000, v19
	v_lshlrev_b32_e32 v184, 16, v12
	v_and_b32_e32 v185, 0xffff0000, v12
	v_lshlrev_b32_e32 v186, 16, v13
	v_and_b32_e32 v187, 0xffff0000, v13
	v_lshlrev_b32_e32 v188, 16, v14
	v_and_b32_e32 v189, 0xffff0000, v14
	v_lshlrev_b32_e32 v190, 16, v15
	v_and_b32_e32 v191, 0xffff0000, v15
	s_waitcnt vmcnt(1)
	v_lshlrev_b32_e32 v192, 16, v8
	v_and_b32_e32 v193, 0xffff0000, v8
	v_lshlrev_b32_e32 v194, 16, v9
	v_and_b32_e32 v195, 0xffff0000, v9
	v_lshlrev_b32_e32 v196, 16, v10
	v_and_b32_e32 v197, 0xffff0000, v10
	v_lshlrev_b32_e32 v198, 16, v11
	v_and_b32_e32 v199, 0xffff0000, v11
	v_lshlrev_b32_e32 v200, 16, v4
	v_and_b32_e32 v201, 0xffff0000, v4
	v_lshlrev_b32_e32 v202, 16, v5
	v_and_b32_e32 v203, 0xffff0000, v5
	v_lshlrev_b32_e32 v204, 16, v6
	v_and_b32_e32 v205, 0xffff0000, v6
	v_lshlrev_b32_e32 v206, 16, v7
	v_and_b32_e32 v207, 0xffff0000, v7
	s_waitcnt vmcnt(0)
	v_lshlrev_b32_e32 v208, 16, v0
	v_and_b32_e32 v209, 0xffff0000, v0
	v_lshlrev_b32_e32 v210, 16, v1
	v_and_b32_e32 v211, 0xffff0000, v1
	v_lshlrev_b32_e32 v212, 16, v2
	v_and_b32_e32 v213, 0xffff0000, v2
	v_lshlrev_b32_e32 v214, 16, v3
	v_and_b32_e32 v215, 0xffff0000, v3
.LBB0_1985:
	s_and_b32 s14, s6, 32
	s_lshl_b32 s4, s14, 4
	v_add_u32_e32 v216, s4, v237
	ds_read_b128 v[0:3], v216 offset:16
	ds_read_b128 v[4:7], v216
	s_and_b32 s4, s10, 64
	s_mul_i32 s5, s4, 0x110
	v_add_u32_e32 v73, s5, v233
	v_lshlrev_b32_e32 v128, 1, v64
	s_add_i32 s6, s6, 16
	s_add_i32 s10, s10, 64
	s_waitcnt lgkmcnt(1)
	v_pk_mul_f32 v[12:13], v[0:1], v[84:85]
	s_waitcnt lgkmcnt(0)
	v_pk_mul_f32 v[8:9], v[4:5], v[80:81]
	v_pk_mul_f32 v[10:11], v[6:7], v[82:83]
	v_pk_mul_f32 v[14:15], v[2:3], v[86:87]
	v_cvt_pk_bf16_f32 v8, v8, v9
	v_cvt_pk_bf16_f32 v9, v10, v11
	v_cvt_pk_bf16_f32 v10, v12, v13
	v_cvt_pk_bf16_f32 v11, v14, v15
	v_pk_mul_f32 v[4:5], v[4:5], v[108:109]
	v_pk_mul_f32 v[6:7], v[6:7], v[110:111]
	v_pk_mul_f32 v[12:13], v[0:1], v[112:113]
	v_pk_mul_f32 v[14:15], v[2:3], v[114:115]
	v_cvt_pk_bf16_f32 v0, v4, v5
	v_cvt_pk_bf16_f32 v1, v6, v7
	v_cvt_pk_bf16_f32 v2, v12, v13
	v_cvt_pk_bf16_f32 v3, v14, v15
	ds_read_b128 v[4:7], v73
	ds_read_b128 v[238:241], v73 offset:32
	s_waitcnt lgkmcnt(1)
	v_mfma_f32_32x32x16_bf16 v[48:63], v[8:11], v[4:7], 0
	v_mfma_f32_32x32x16_bf16 v[16:31], v[0:3], v[4:7], 0
	ds_read_b128 v[4:7], v73 offset:8704
	ds_read_b128 v[242:245], v216 offset:80
	ds_read_b128 v[246:249], v216 offset:64
	s_waitcnt lgkmcnt(1)
	v_mul_f32_e64 v250, v242, v92
	v_mul_f32_e64 v251, v243, v93
	s_waitcnt lgkmcnt(0)
	v_pk_mul_f32 v[224:225], v[246:247], v[88:89]
	v_pk_mul_f32 v[226:227], v[248:249], v[90:91]
	v_pk_mul_f32 v[222:223], v[244:245], v[94:95]
	v_cvt_pk_bf16_f32 v224, v224, v225
	v_cvt_pk_bf16_f32 v225, v226, v227
	v_cvt_pk_bf16_f32 v226, v250, v251
	v_cvt_pk_bf16_f32 v227, v222, v223
	v_pk_mul_f32 v[222:223], v[246:247], v[116:117]
	v_pk_mul_f32 v[246:247], v[248:249], v[118:119]
	v_pk_mul_f32 v[248:249], v[242:243], v[120:121]
	v_pk_mul_f32 v[250:251], v[244:245], v[122:123]
	v_cvt_pk_bf16_f32 v242, v222, v223
	v_cvt_pk_bf16_f32 v243, v246, v247
	v_cvt_pk_bf16_f32 v244, v248, v249
	v_cvt_pk_bf16_f32 v245, v250, v251
	s_waitcnt lgkmcnt(0)
	v_mfma_f32_32x32x16_bf16 v[32:47], v[8:11], v[4:7], 0
	v_mfma_f32_32x32x16_bf16 v[0:15], v[0:3], v[4:7], 0
	v_mfma_f32_32x32x16_bf16 v[48:63], v[224:227], v[238:241], v[48:63]
	v_mfma_f32_32x32x16_bf16 v[16:31], v[242:245], v[238:241], v[16:31]
	ds_read_b128 v[238:241], v73 offset:8736
	s_waitcnt lgkmcnt(0)
	v_mfma_f32_32x32x16_bf16 v[32:47], v[224:227], v[238:241], v[32:47]
	v_mfma_f32_32x32x16_bf16 v[0:15], v[242:245], v[238:241], v[0:15]
	ds_read_b128 v[224:227], v216 offset:144
	ds_read_b128 v[238:241], v216 offset:128
	s_waitcnt lgkmcnt(1)
	v_mul_f32_e64 v246, v224, v100
	v_mul_f32_e64 v247, v225, v101
	s_waitcnt lgkmcnt(0)
	v_pk_mul_f32 v[222:223], v[238:239], v[96:97]
	v_pk_mul_f32 v[244:245], v[240:241], v[98:99]
	v_pk_mul_f32 v[248:249], v[226:227], v[102:103]
	v_cvt_pk_bf16_f32 v242, v222, v223
	v_cvt_pk_bf16_f32 v243, v244, v245
	v_cvt_pk_bf16_f32 v244, v246, v247
	v_pk_mul_f32 v[222:223], v[238:239], v[124:125]
	v_pk_mul_f32 v[238:239], v[240:241], v[126:127]
	v_pk_mul_f32 v[240:241], v[224:225], v[130:131]
	v_pk_mul_f32 v[246:247], v[226:227], v[132:133]
	v_cvt_pk_bf16_f32 v245, v248, v249
	v_cvt_pk_bf16_f32 v224, v222, v223
	v_cvt_pk_bf16_f32 v225, v238, v239
	v_cvt_pk_bf16_f32 v226, v240, v241
	v_cvt_pk_bf16_f32 v227, v246, v247
	ds_read_b128 v[238:241], v73 offset:64
	s_waitcnt lgkmcnt(0)
	v_mfma_f32_32x32x16_bf16 v[48:63], v[242:245], v[238:241], v[48:63]
	v_mfma_f32_32x32x16_bf16 v[16:31], v[224:227], v[238:241], v[16:31]
	ds_read_b128 v[238:241], v73 offset:8768
	s_waitcnt lgkmcnt(0)
	v_mfma_f32_32x32x16_bf16 v[32:47], v[242:245], v[238:241], v[32:47]
	v_mfma_f32_32x32x16_bf16 v[0:15], v[224:227], v[238:241], v[0:15]
	ds_read_b128 v[224:227], v216 offset:208
	ds_read_b128 v[238:241], v216 offset:192
	s_waitcnt lgkmcnt(1)
	v_mul_f32_e64 v246, v224, v134
	v_mul_f32_e64 v247, v225, v135
	s_waitcnt lgkmcnt(0)
	v_pk_mul_f32 v[222:223], v[238:239], v[104:105]
	v_pk_mul_f32 v[244:245], v[240:241], v[106:107]
	v_pk_mul_f32 v[248:249], v[226:227], v[136:137]
	v_cvt_pk_bf16_f32 v242, v222, v223
	v_cvt_pk_bf16_f32 v243, v244, v245
	v_cvt_pk_bf16_f32 v244, v246, v247
	v_pk_mul_f32 v[222:223], v[238:239], v[138:139]
	v_pk_mul_f32 v[238:239], v[240:241], v[140:141]
	v_pk_mul_f32 v[240:241], v[224:225], v[142:143]
	v_pk_mul_f32 v[246:247], v[226:227], v[144:145]
	v_cvt_pk_bf16_f32 v245, v248, v249
	v_cvt_pk_bf16_f32 v224, v222, v223
	v_cvt_pk_bf16_f32 v225, v238, v239
	v_cvt_pk_bf16_f32 v226, v240, v241
	v_cvt_pk_bf16_f32 v227, v246, v247
	ds_read_b128 v[238:241], v73 offset:96
	s_waitcnt lgkmcnt(0)
	v_mfma_f32_32x32x16_bf16 v[48:63], v[242:245], v[238:241], v[48:63]
	v_mfma_f32_32x32x16_bf16 v[16:31], v[224:227], v[238:241], v[16:31]
	ds_read_b128 v[238:241], v73 offset:8800
	s_waitcnt lgkmcnt(0)
	v_mfma_f32_32x32x16_bf16 v[32:47], v[242:245], v[238:241], v[32:47]
	v_mfma_f32_32x32x16_bf16 v[0:15], v[224:227], v[238:241], v[0:15]
	ds_read_b128 v[224:227], v216 offset:272
	ds_read_b128 v[238:241], v216 offset:256
	s_waitcnt lgkmcnt(1)
	v_mul_f32_e64 v246, v224, v150
	v_mul_f32_e64 v247, v225, v151
	s_waitcnt lgkmcnt(0)
	v_pk_mul_f32 v[222:223], v[238:239], v[146:147]
	v_pk_mul_f32 v[244:245], v[240:241], v[148:149]
	v_pk_mul_f32 v[248:249], v[226:227], v[152:153]
	v_cvt_pk_bf16_f32 v242, v222, v223
	v_cvt_pk_bf16_f32 v243, v244, v245
	v_cvt_pk_bf16_f32 v244, v246, v247
	v_pk_mul_f32 v[222:223], v[238:239], v[154:155]
	v_pk_mul_f32 v[238:239], v[240:241], v[156:157]
	v_pk_mul_f32 v[240:241], v[224:225], v[158:159]
	v_pk_mul_f32 v[246:247], v[226:227], v[160:161]
	v_cvt_pk_bf16_f32 v245, v248, v249
	v_cvt_pk_bf16_f32 v224, v222, v223
	v_cvt_pk_bf16_f32 v225, v238, v239
	v_cvt_pk_bf16_f32 v226, v240, v241
	v_cvt_pk_bf16_f32 v227, v246, v247
	ds_read_b128 v[238:241], v73 offset:128
	s_waitcnt lgkmcnt(0)
	v_mfma_f32_32x32x16_bf16 v[48:63], v[242:245], v[238:241], v[48:63]
	v_mfma_f32_32x32x16_bf16 v[16:31], v[224:227], v[238:241], v[16:31]
	ds_read_b128 v[238:241], v73 offset:8832
	s_waitcnt lgkmcnt(0)
	v_mfma_f32_32x32x16_bf16 v[32:47], v[242:245], v[238:241], v[32:47]
	v_mfma_f32_32x32x16_bf16 v[0:15], v[224:227], v[238:241], v[0:15]
	ds_read_b128 v[224:227], v216 offset:336
	ds_read_b128 v[238:241], v216 offset:320
	s_waitcnt lgkmcnt(1)
	v_mul_f32_e64 v246, v224, v172
	v_mul_f32_e64 v247, v225, v173
	s_waitcnt lgkmcnt(0)
	v_pk_mul_f32 v[222:223], v[238:239], v[168:169]
	v_pk_mul_f32 v[244:245], v[240:241], v[170:171]
	v_pk_mul_f32 v[248:249], v[226:227], v[174:175]
	v_cvt_pk_bf16_f32 v242, v222, v223
	v_cvt_pk_bf16_f32 v243, v244, v245
	v_cvt_pk_bf16_f32 v244, v246, v247
	v_pk_mul_f32 v[222:223], v[238:239], v[176:177]
	v_pk_mul_f32 v[238:239], v[240:241], v[178:179]
	v_pk_mul_f32 v[240:241], v[224:225], v[180:181]
	v_pk_mul_f32 v[246:247], v[226:227], v[182:183]
	v_cvt_pk_bf16_f32 v245, v248, v249
	v_cvt_pk_bf16_f32 v224, v222, v223
	v_cvt_pk_bf16_f32 v225, v238, v239
	v_cvt_pk_bf16_f32 v226, v240, v241
	v_cvt_pk_bf16_f32 v227, v246, v247
	ds_read_b128 v[238:241], v73 offset:160
	s_waitcnt lgkmcnt(0)
	v_mfma_f32_32x32x16_bf16 v[48:63], v[242:245], v[238:241], v[48:63]
	v_mfma_f32_32x32x16_bf16 v[16:31], v[224:227], v[238:241], v[16:31]
	ds_read_b128 v[238:241], v73 offset:8864
	s_waitcnt lgkmcnt(0)
	v_mfma_f32_32x32x16_bf16 v[32:47], v[242:245], v[238:241], v[32:47]
	v_mfma_f32_32x32x16_bf16 v[0:15], v[224:227], v[238:241], v[0:15]
	ds_read_b128 v[224:227], v216 offset:400
	ds_read_b128 v[238:241], v216 offset:384
	s_waitcnt lgkmcnt(1)
	v_mul_f32_e64 v246, v224, v188
	v_mul_f32_e64 v247, v225, v189
	s_waitcnt lgkmcnt(0)
	v_pk_mul_f32 v[222:223], v[238:239], v[184:185]
	v_pk_mul_f32 v[244:245], v[240:241], v[186:187]
	v_pk_mul_f32 v[248:249], v[226:227], v[190:191]
	v_cvt_pk_bf16_f32 v242, v222, v223
	v_cvt_pk_bf16_f32 v243, v244, v245
	v_cvt_pk_bf16_f32 v244, v246, v247
	v_pk_mul_f32 v[222:223], v[238:239], v[192:193]
	v_pk_mul_f32 v[238:239], v[240:241], v[194:195]
	v_pk_mul_f32 v[240:241], v[224:225], v[196:197]
	v_pk_mul_f32 v[246:247], v[226:227], v[198:199]
	v_cvt_pk_bf16_f32 v245, v248, v249
	v_cvt_pk_bf16_f32 v224, v222, v223
	v_cvt_pk_bf16_f32 v225, v238, v239
	v_cvt_pk_bf16_f32 v226, v240, v241
	v_cvt_pk_bf16_f32 v227, v246, v247
	ds_read_b128 v[238:241], v73 offset:192
	s_waitcnt lgkmcnt(0)
	v_mfma_f32_32x32x16_bf16 v[48:63], v[242:245], v[238:241], v[48:63]
	v_mfma_f32_32x32x16_bf16 v[16:31], v[224:227], v[238:241], v[16:31]
	ds_read_b128 v[238:241], v73 offset:8896
	s_waitcnt lgkmcnt(0)
	v_mfma_f32_32x32x16_bf16 v[32:47], v[242:245], v[238:241], v[32:47]
	v_mfma_f32_32x32x16_bf16 v[0:15], v[224:227], v[238:241], v[0:15]
	ds_read_b128 v[224:227], v216 offset:464
	ds_read_b128 v[238:241], v216 offset:448
	s_waitcnt lgkmcnt(1)
	v_mul_f32_e64 v244, v224, v204
	v_mul_f32_e64 v245, v225, v205
	s_waitcnt lgkmcnt(0)
	v_pk_mul_f32 v[216:217], v[238:239], v[200:201]
	v_pk_mul_f32 v[222:223], v[240:241], v[202:203]
	v_pk_mul_f32 v[246:247], v[226:227], v[206:207]
	v_cvt_pk_bf16_f32 v242, v216, v217
	v_cvt_pk_bf16_f32 v243, v222, v223
	v_pk_mul_f32 v[216:217], v[238:239], v[208:209]
	v_pk_mul_f32 v[222:223], v[240:241], v[210:211]
	v_pk_mul_f32 v[238:239], v[224:225], v[212:213]
	v_pk_mul_f32 v[240:241], v[226:227], v[214:215]
	v_cvt_pk_bf16_f32 v244, v244, v245
	v_cvt_pk_bf16_f32 v245, v246, v247
	v_cvt_pk_bf16_f32 v226, v238, v239
	v_cvt_pk_bf16_f32 v227, v240, v241
	ds_read_b128 v[238:241], v73 offset:224
	s_waitcnt lgkmcnt(0)
	v_mfma_f32_32x32x16_bf16 v[48:63], v[242:245], v[238:241], v[48:63]
	v_cvt_pk_bf16_f32 v224, v216, v217
	v_cvt_pk_bf16_f32 v225, v222, v223
	v_lshl_add_u64 v[216:217], v[78:79], 0, s[14:15]
	v_lshlrev_b64 v[216:217], 14, v[216:217]
	v_lshl_add_u64 v[216:217], v[70:71], 0, v[216:217]
	s_lshl_b32 s14, s4, 1
	v_lshl_add_u64 v[216:217], v[216:217], 0, s[14:15]
	v_mfma_f32_32x32x16_bf16 v[16:31], v[224:227], v[238:241], v[16:31]
	ds_read_b128 v[238:241], v73 offset:8928
	v_lshl_add_u64 v[216:217], v[216:217], 0, v[128:129]
	s_nop 1
	v_cvt_pk_bf16_f32 v48, v48, s0
	global_store_short v[216:217], v48, off
	v_cvt_pk_bf16_f32 v48, v49, s0
	global_store_short v[216:217], v48, off offset:256
	v_cvt_pk_bf16_f32 v48, v50, s0
	global_store_short v[216:217], v48, off offset:512
	v_cvt_pk_bf16_f32 v48, v51, s0
	s_waitcnt lgkmcnt(0)
	v_mfma_f32_32x32x16_bf16 v[32:47], v[242:245], v[238:241], v[32:47]
	global_store_short v[216:217], v48, off offset:768
	v_cvt_pk_bf16_f32 v48, v52, s0
	global_store_short v[216:217], v48, off offset:2048
	v_cvt_pk_bf16_f32 v48, v53, s0
	global_store_short v[216:217], v48, off offset:2304
	v_cvt_pk_bf16_f32 v48, v54, s0
	global_store_short v[216:217], v48, off offset:2560
	v_mfma_f32_32x32x16_bf16 v[0:15], v[224:227], v[238:241], v[0:15]
	v_cvt_pk_bf16_f32 v48, v55, s0
	global_store_short v[216:217], v48, off offset:2816
	v_add_co_u32_e64 v48, s[4:5], s12, v216
	v_cvt_pk_bf16_f32 v16, v16, s0
	s_nop 0
	v_addc_co_u32_e64 v49, s[4:5], 0, v217, s[4:5]
	v_add_co_u32_e64 v50, s[4:5], s11, v216
	v_cvt_pk_bf16_f32 v32, v32, s0
	s_nop 0
	v_addc_co_u32_e64 v51, s[4:5], 0, v217, s[4:5]
	global_store_short v[50:51], v16, off
	v_cvt_pk_bf16_f32 v16, v17, s0
	v_cvt_pk_bf16_f32 v0, v0, s0
	global_store_short v[216:217], v32, off offset:64
	v_cvt_pk_bf16_f32 v32, v33, s0
	global_store_short v[50:51], v16, off offset:256
	v_cvt_pk_bf16_f32 v16, v18, s0
	global_store_short v[50:51], v0, off offset:64
	v_cvt_pk_bf16_f32 v0, v1, s0
	global_store_short v[216:217], v32, off offset:320
	v_cvt_pk_bf16_f32 v32, v34, s0
	global_store_short v[50:51], v16, off offset:512
	v_cvt_pk_bf16_f32 v16, v19, s0
	global_store_short v[50:51], v0, off offset:320
	v_cvt_pk_bf16_f32 v0, v2, s0
	global_store_short v[216:217], v32, off offset:576
	v_cvt_pk_bf16_f32 v32, v35, s0
	global_store_short v[50:51], v16, off offset:768
	v_cvt_pk_bf16_f32 v16, v20, s0
	global_store_short v[50:51], v0, off offset:576
	v_cvt_pk_bf16_f32 v0, v3, s0
	global_store_short v[216:217], v32, off offset:832
	v_cvt_pk_bf16_f32 v32, v36, s0
	global_store_short v[50:51], v16, off offset:2048
	v_cvt_pk_bf16_f32 v16, v21, s0
	global_store_short v[50:51], v0, off offset:832
	v_cvt_pk_bf16_f32 v0, v4, s0
	global_store_short v[216:217], v32, off offset:2112
	v_cvt_pk_bf16_f32 v32, v37, s0
	global_store_short v[50:51], v16, off offset:2304
	v_cvt_pk_bf16_f32 v16, v22, s0
	global_store_short v[50:51], v0, off offset:2112
	v_cvt_pk_bf16_f32 v0, v5, s0
	global_store_short v[216:217], v32, off offset:2368
	v_cvt_pk_bf16_f32 v32, v38, s0
	global_store_short v[50:51], v16, off offset:2560
	v_cvt_pk_bf16_f32 v16, v23, s0
	global_store_short v[50:51], v0, off offset:2368
	v_cvt_pk_bf16_f32 v0, v6, s0
	global_store_short v[216:217], v32, off offset:2624
	v_cvt_pk_bf16_f32 v32, v39, s0
	global_store_short v[50:51], v16, off offset:2816
	v_add_co_u32_e64 v16, s[4:5], s7, v216
	global_store_short v[50:51], v0, off offset:2624
	v_cvt_pk_bf16_f32 v0, v7, s0
	v_cvt_pk_bf16_f32 v52, v56, s0
	global_store_short v[216:217], v32, off offset:2880
	v_cvt_pk_bf16_f32 v32, v40, s0
	v_cvt_pk_bf16_f32 v18, v24, s0
	v_addc_co_u32_e64 v17, s[4:5], 0, v217, s[4:5]
	global_store_short v[50:51], v0, off offset:2880
	v_cvt_pk_bf16_f32 v0, v8, s0
	global_store_short v[50:51], v52, off offset:-4096
	v_cvt_pk_bf16_f32 v52, v57, s0
	global_store_short v[48:49], v32, off offset:64
	v_cvt_pk_bf16_f32 v32, v41, s0
	global_store_short v[16:17], v18, off
	v_cvt_pk_bf16_f32 v18, v25, s0
	global_store_short v[16:17], v0, off offset:64
	v_cvt_pk_bf16_f32 v0, v9, s0
	global_store_short v[48:49], v52, off offset:256
	v_cvt_pk_bf16_f32 v52, v58, s0
	global_store_short v[48:49], v32, off offset:320
	v_cvt_pk_bf16_f32 v32, v42, s0
	global_store_short v[16:17], v18, off offset:256
	v_cvt_pk_bf16_f32 v18, v26, s0
	global_store_short v[16:17], v0, off offset:320
	v_cvt_pk_bf16_f32 v0, v10, s0
	global_store_short v[48:49], v52, off offset:512
	v_cvt_pk_bf16_f32 v52, v59, s0
	global_store_short v[48:49], v32, off offset:576
	v_cvt_pk_bf16_f32 v32, v43, s0
	global_store_short v[16:17], v18, off offset:512
	v_cvt_pk_bf16_f32 v18, v27, s0
	global_store_short v[16:17], v0, off offset:576
	v_cvt_pk_bf16_f32 v0, v11, s0
	global_store_short v[48:49], v52, off offset:768
	v_cvt_pk_bf16_f32 v52, v60, s0
	global_store_short v[48:49], v32, off offset:832
	v_cvt_pk_bf16_f32 v32, v44, s0
	global_store_short v[16:17], v18, off offset:768
	v_cvt_pk_bf16_f32 v18, v28, s0
	global_store_short v[16:17], v0, off offset:832
	v_cvt_pk_bf16_f32 v0, v12, s0
	global_store_short v[48:49], v52, off offset:2048
	v_cvt_pk_bf16_f32 v52, v61, s0
	global_store_short v[48:49], v32, off offset:2112
	v_cvt_pk_bf16_f32 v32, v45, s0
	global_store_short v[16:17], v18, off offset:2048
	v_cvt_pk_bf16_f32 v18, v29, s0
	global_store_short v[16:17], v0, off offset:2112
	v_cvt_pk_bf16_f32 v0, v13, s0
	global_store_short v[48:49], v52, off offset:2304
	v_cvt_pk_bf16_f32 v52, v62, s0
	global_store_short v[48:49], v32, off offset:2368
	v_cvt_pk_bf16_f32 v32, v46, s0
	global_store_short v[16:17], v18, off offset:2304
	v_cvt_pk_bf16_f32 v18, v30, s0
	global_store_short v[16:17], v0, off offset:2368
	v_cvt_pk_bf16_f32 v0, v14, s0
	global_store_short v[48:49], v52, off offset:2560
	v_cvt_pk_bf16_f32 v52, v63, s0
	global_store_short v[48:49], v32, off offset:2624
	v_cvt_pk_bf16_f32 v32, v47, s0
	global_store_short v[16:17], v18, off offset:2560
	v_cvt_pk_bf16_f32 v18, v31, s0
	global_store_short v[16:17], v0, off offset:2624
	v_cvt_pk_bf16_f32 v0, v15, s0
	s_cmp_eq_u32 s6, 64
	global_store_short v[48:49], v52, off offset:2816
	global_store_short v[48:49], v32, off offset:2880
	global_store_short v[16:17], v18, off offset:2816
	global_store_short v[16:17], v0, off offset:2880
	s_cbranch_scc0 .LBB0_1985
	v_writelane_b32 v252, s14, 12
	s_nop 1
	v_writelane_b32 v252, s15, 13
	s_nop 0
	v_readlane_b32 s4, v252, 2
	s_add_i32 s16, s16, s4
	s_cmpk_gt_i32 s16, 0x3ff
	s_cbranch_scc0 .LBB0_1978
